# B1X on FP: prologue bias1 dot products spread over all workgroups (one output per workgroup, all loads in flight at once) instead of a serial 8-round chain on 32 workgroups
# speedup vs baseline: 1.0163x; 1.0065x over previous
.LBB0_19:
	s_or_b64 exec, exec, s[0:1]
	s_mov_b64 vcc, exec
	s_and_saveexec_b64 s[0:1], vcc
	s_waitcnt lgkmcnt(0)
	v_writelane_b32 v234, s16, 20
	s_nop 1
	v_writelane_b32 v234, s17, 21
	v_writelane_b32 v234, s18, 22
	v_writelane_b32 v234, s19, 23
	v_writelane_b32 v234, s20, 24
	v_writelane_b32 v234, s21, 25
	v_writelane_b32 v234, s22, 26
	v_writelane_b32 v234, s23, 27
	v_writelane_b32 v234, s24, 28
	v_writelane_b32 v234, s25, 29
	v_writelane_b32 v234, s26, 30
	v_writelane_b32 v234, s27, 31
	v_writelane_b32 v234, s28, 32
	v_writelane_b32 v234, s29, 33
	v_writelane_b32 v234, s30, 34
	v_writelane_b32 v234, s31, 35
	s_cbranch_execz .LBB0_24
	v_readlane_b32 s18, v234, 8
	v_readlane_b32 s19, v234, 9
	v_readlane_b32 s20, v234, 10
	v_readlane_b32 s21, v234, 11
	v_readlane_b32 s22, v234, 12
	v_readlane_b32 s23, v234, 13
	v_readlane_b32 s26, v234, 16
	v_readlane_b32 s27, v234, 17
	s_nop 3
	s_and_b32 s12, s74, 0x80
	s_cmp_eq_u32 s12, 0
	s_cselect_b32 s14, s18, s20
	s_cselect_b32 s15, s19, s21
	s_cselect_b32 s16, s22, s26
	s_cselect_b32 s17, s23, s27
	s_lshr_b32 s12, s74, 8
	s_lshl_b32 s13, s12, 13
	s_add_u32 s14, s14, s13
	s_addc_u32 s15, s15, 0
	s_lshl_b32 s13, s12, 20
	s_add_u32 s16, s16, s13
	s_addc_u32 s17, s17, 0
	s_and_b32 s12, s74, 0x7f
	s_lshl_b32 s12, s12, 2
	s_add_u32 s16, s16, s12
	s_addc_u32 s17, s17, 0
	v_lshlrev_b32_e32 v0, 5, v156
	v_lshlrev_b32_e32 v1, 12, v156
	global_load_dwordx4 v[8:11], v0, s[14:15]
	global_load_dwordx4 v[12:15], v0, s[14:15] offset:16
	global_load_dword v16, v1, s[16:17]
	global_load_dword v17, v1, s[16:17] offset:512
	global_load_dword v18, v1, s[16:17] offset:1024
	global_load_dword v19, v1, s[16:17] offset:1536
	global_load_dword v20, v1, s[16:17] offset:2048
	global_load_dword v21, v1, s[16:17] offset:2560
	global_load_dword v22, v1, s[16:17] offset:3072
	global_load_dword v23, v1, s[16:17] offset:3584
	s_waitcnt vmcnt(0)
	v_mul_f32_e32 v2, v8, v16
	v_fmac_f32_e32 v2, v9, v17
	v_fmac_f32_e32 v2, v10, v18
	v_fmac_f32_e32 v2, v11, v19
	v_fmac_f32_e32 v2, v12, v20
	v_fmac_f32_e32 v2, v13, v21
	v_fmac_f32_e32 v2, v14, v22
	v_fmac_f32_e32 v2, v15, v23
	s_nop 1
	v_add_f32_dpp v2, v2, v2 quad_perm:[1,0,3,2] row_mask:0xf bank_mask:0xf
	s_nop 1
	v_add_f32_dpp v2, v2, v2 quad_perm:[2,3,0,1] row_mask:0xf bank_mask:0xf
	s_nop 1
	v_add_f32_dpp v2, v2, v2 row_half_mirror row_mask:0xf bank_mask:0xf
	s_nop 1
	v_add_f32_dpp v2, v2, v2 row_mirror row_mask:0xf bank_mask:0xf
	s_nop 1
	v_readlane_b32 s12, v2, 0
	v_readlane_b32 s13, v2, 16
	v_readlane_b32 s6, v2, 32
	v_readlane_b32 s7, v2, 48
	s_nop 1
	v_mov_b32_e32 v3, s12
	v_add_f32_e32 v3, s13, v3
	v_add_f32_e32 v3, s6, v3
	v_add_f32_e32 v3, s7, v3
	v_lshrrev_b32_e32 v0, 6, v156
	v_lshlrev_b32_e32 v0, 2, v0
	ds_write_b32 v0, v3
	s_waitcnt lgkmcnt(0)
	s_barrier
	v_mov_b32_e32 v0, 0
	ds_read_b128 v[8:11], v0
	s_lshl_b32 s12, s74, 2
	s_add_u32 s12, s12, 0x2000
	s_add_u32 s12, s80, s12
	s_addc_u32 s13, s81, 0
	s_waitcnt lgkmcnt(0)
	v_add_f32_e32 v2, v8, v9
	v_add_f32_e32 v2, v2, v10
	v_add_f32_e32 v2, v2, v11
	v_cmp_eq_u32_e32 vcc, 0, v156
	s_and_saveexec_b64 s[6:7], vcc
	global_store_dword v0, v2, s[12:13]
	s_or_b64 exec, exec, s[6:7]
	s_barrier
	v_readlane_b32 s12, v234, 20
	v_readlane_b32 s13, v234, 21
	v_readlane_b32 s14, v234, 22
	v_readlane_b32 s15, v234, 23
	v_readlane_b32 s16, v234, 24
	v_readlane_b32 s17, v234, 25
	v_readlane_b32 s18, v234, 26
	v_readlane_b32 s19, v234, 27
	v_readlane_b32 s20, v234, 28
	v_readlane_b32 s21, v234, 29
	v_readlane_b32 s22, v234, 30
	v_readlane_b32 s23, v234, 31
	v_readlane_b32 s24, v234, 32
	v_readlane_b32 s25, v234, 33
	v_readlane_b32 s26, v234, 34
	v_readlane_b32 s27, v234, 35
